# ffn-up next-unit computed incrementally (pn+8, wrap 22 -> pm+4)
# speedup vs baseline: 1.0171x; 1.0060x over previous
;     __device__ bool next(int i, Unit& u) const {
;         const long L = (long)i * G + c; if (L >= nwg) return false;
;         int wgid = (int)L; { const int q = nwg / NXCD, r = nwg % NXCD, xcd = wgid % NXCD, off = wgid / NXCD; wgid = (xcd < r ? xcd * (q + 1) : r * (q + 1) + (xcd - r) * q) + off; }
;         const int nig = wgm * nN, gid = wgid / nig, fm = gid * wgm, gsz = (nM - fm) < wgm ? (nM - fm) : wgm;
;         u.pm = fm + ((wgid % nig) % gsz); u.pn = (wgid % nig) / gsz; return true;
; template <class Epi>
; __device__ __forceinline__ void gemm_phase(LAS unsigned char* lds, const Gemm g, const StaticOrder& S, const Epi& E, const int tid) {
;     ...
;         const bool has_next = S.next(ui + 1, nxt);
.LBB0_644:
	s_add_i32 s73, s73, 1
	s_mov_b32 s91, -1
	s_cmp_lt_u32 s73, 11
	s_cselect_b64 s[6:7], -1, 0
	s_cbranch_scc0 .LBB0_646
	s_add_i32 s91, s51, 8
	s_mov_b32 s20, s89
	s_cmp_lt_i32 s91, 22
	s_cbranch_scc1 .Lffn_nx
	s_sub_i32 s91, s91, 22
	s_add_i32 s20, s89, 4
.Lffn_nx:
	s_mov_b32 s90, s91
